# DeltaNet level-1 scan step: LDS reads hoisted ahead of MFMA chains, hardware bf16 pack instead of bit trick, dead zero-inits removed
# speedup vs baseline: 1.5051x; 1.0261x over previous
.LBB0_477:
	s_or_b64 exec, exec, s[4:5]
	s_waitcnt lgkmcnt(0)
	s_barrier
	s_nop 1
	ds_read_b128 v[16:19], v178 offset:8704
	ds_read_b128 v[20:23], v178 offset:8736
	ds_read_b128 v[24:27], v178 offset:8768
	ds_read_b128 v[28:31], v178 offset:8800
	v_pk_mul_f32 v[14:15], v[144:145], v[14:15] op_sel_hi:[0,1]
	v_pk_mul_f32 v[12:13], v[144:145], v[12:13] op_sel_hi:[0,1]
	v_pk_mul_f32 v[10:11], v[144:145], v[10:11] op_sel_hi:[0,1]
	v_pk_mul_f32 v[8:9], v[144:145], v[8:9] op_sel_hi:[0,1]
	v_pk_mul_f32 v[6:7], v[144:145], v[6:7] op_sel_hi:[0,1]
	v_pk_mul_f32 v[4:5], v[144:145], v[4:5] op_sel_hi:[0,1]
	v_pk_mul_f32 v[2:3], v[144:145], v[2:3] op_sel_hi:[0,1]
	v_pk_mul_f32 v[0:1], v[144:145], v[0:1] op_sel_hi:[0,1]
	s_waitcnt lgkmcnt(3)
	s_nop 0
	v_mfma_f32_32x32x16_bf16 v[0:15], v[118:121], v[16:19], v[0:15]
	s_waitcnt lgkmcnt(2)
	v_mfma_f32_32x32x16_bf16 v[0:15], v[114:117], v[20:23], v[0:15]
	s_waitcnt lgkmcnt(1)
	v_mfma_f32_32x32x16_bf16 v[0:15], v[102:105], v[24:27], v[0:15]
	s_waitcnt lgkmcnt(0)
	v_mfma_f32_32x32x16_bf16 v[0:15], v[98:101], v[28:31], v[0:15]
	s_and_b64 s[4:5], s[10:11], exec
	s_cselect_b32 s10, 0x80, s15
	s_add_i32 s6, s10, s14
	s_lshl_b64 s[20:21], s[6:7], 14
	v_lshl_add_u64 v[16:17], v[162:163], 0, s[20:21]
	v_add_co_u32_e64 v18, s[4:5], s18, v16
	v_lshl_add_u64 v[20:21], v[164:165], 0, s[20:21]
	s_nop 0
	v_addc_co_u32_e64 v19, s[4:5], 0, v17, s[4:5]
	global_load_dwordx4 v[98:101], v[18:19], off offset:-4096
	global_load_dwordx4 v[102:105], v[18:19], off
	v_add_co_u32_e64 v18, s[4:5], s19, v16
	s_ashr_i32 s11, s10, 31
	s_nop 0
	v_addc_co_u32_e64 v19, s[4:5], 0, v17, s[4:5]
	global_load_dwordx4 v[114:117], v[18:19], off
	global_load_dwordx4 v[118:121], v[20:21], off
	v_add_co_u32_e64 v18, s[4:5], s18, v20
	s_nop 1
	v_addc_co_u32_e64 v19, s[4:5], 0, v21, s[4:5]
	global_load_dwordx4 v[122:125], v[18:19], off offset:-4096
	global_load_dwordx4 v[126:129], v[18:19], off
	v_add_co_u32_e64 v18, s[4:5], s19, v20
	s_nop 1
	v_addc_co_u32_e64 v19, s[4:5], 0, v21, s[4:5]
	s_lshl_b64 s[4:5], s[10:11], 2
	s_add_u32 s4, s16, s4
	v_lshl_add_u64 v[20:21], v[166:167], 0, s[20:21]
	global_load_dwordx4 v[134:137], v[18:19], off
	global_load_dwordx4 v[138:141], v[20:21], off
	s_addc_u32 s5, s17, s5
	global_load_dwordx4 v[130:133], v[16:17], off
	global_load_dword v144, v157, s[4:5]
	s_add_u32 s8, s8, 0x10000
	s_addc_u32 s9, s9, 0
	s_add_i32 s15, s15, 3
	s_cmp_lg_u32 s8, 0x2b0000
	s_waitcnt vmcnt(20)
	v_mov_b32_e32 v142, v177
	s_cbranch_scc0 .LBB0_496
.LBB0_478:
	v_lshl_add_u64 v[16:17], v[168:169], 0, s[8:9]
	s_mov_b32 s4, 0x7489000
	v_add_co_u32_e64 v18, s[4:5], s4, v16
	v_add_u32_e32 v179, 0xe800, v174
	s_nop 0
	v_addc_co_u32_e64 v19, s[4:5], 0, v17, s[4:5]
	s_mov_b32 s4, 0x748a000
	s_nop 0
	v_add_co_u32_e64 v20, s[4:5], s4, v16
	s_nop 1
	v_addc_co_u32_e64 v21, s[4:5], 0, v17, s[4:5]
	s_mov_b32 s4, 0x748b000
	global_store_dword v[20:21], v0, off offset:-4096 nt
	global_store_dword v[18:19], v1, off offset:512 nt
	global_store_dword v[18:19], v2, off offset:1024 nt
	global_store_dword v[18:19], v3, off offset:1536 nt
	global_store_dword v[20:21], v4, off nt
	global_store_dword v[20:21], v5, off offset:512 nt
	global_store_dword v[20:21], v6, off offset:1024 nt
	global_store_dword v[20:21], v7, off offset:1536 nt
	v_add_co_u32_e64 v18, s[4:5], s4, v16
	s_nop 0
	v_addc_co_u32_e64 v19, s[4:5], 0, v17, s[4:5]
	s_mov_b32 s4, 0x748c000
	s_nop 0
	v_add_co_u32_e64 v16, s[4:5], s4, v16
	s_nop 0
	v_addc_co_u32_e64 v17, s[4:5], 0, v17, s[4:5]
	global_store_dword v[16:17], v8, off offset:-4096 nt
	global_store_dword v[18:19], v9, off offset:512 nt
	global_store_dword v[18:19], v10, off offset:1024 nt
	global_store_dword v[18:19], v11, off offset:1536 nt
	global_store_dword v[16:17], v12, off nt
	global_store_dword v[16:17], v13, off offset:512 nt
	global_store_dword v[16:17], v14, off offset:1024 nt
	global_store_dword v[16:17], v15, off offset:1536 nt
	s_waitcnt vmcnt(41)
	ds_write_b128 v146, v[64:67] offset:24576
	ds_write_b128 v148, v[32:35] offset:24576
	ds_write_b128 v150, v[36:39] offset:24576
	s_waitcnt vmcnt(40)
	ds_write_b128 v152, v[40:43] offset:24576
	s_waitcnt vmcnt(37)
	ds_write_b128 v154, v[44:47] offset:41984
	ds_write_b128 v156, v[48:51] offset:41984
	ds_write_b128 v158, v[52:55] offset:41984
	s_waitcnt vmcnt(36)
	ds_write_b128 v160, v[68:71] offset:41984
	s_waitcnt vmcnt(35)
	ds_write_b128 v154, v[82:85] offset:60416
	v_cvt_pk_bf16_f32 v16, v0, v1
	v_cvt_pk_bf16_f32 v17, v2, v3
	v_cvt_pk_bf16_f32 v18, v4, v5
	v_cvt_pk_bf16_f32 v19, v6, v7
	ds_write2_b64 v159, v[16:17], v[18:19] offset1:2
	v_cvt_pk_bf16_f32 v16, v8, v9
	v_cvt_pk_bf16_f32 v17, v10, v11
	v_cvt_pk_bf16_f32 v18, v12, v13
	v_cvt_pk_bf16_f32 v19, v14, v15
	ds_write2_b64 v159, v[16:17], v[18:19] offset0:4 offset1:6
	s_waitcnt lgkmcnt(0)
	s_barrier
	ds_read_b128 v[44:47], v161 offset:41984
	ds_read_b128 v[40:43], v161 offset:42016
	ds_read_b128 v[36:39], v161 offset:42048
	ds_read_b128 v[32:35], v161 offset:42080
	s_and_saveexec_b64 s[4:5], vcc
	s_cbranch_execz .LBB0_480
	ds_read2_b64 v[52:55], v179 offset0:128 offset1:130
	ds_read2_b64 v[48:51], v179 offset0:132 offset1:134
.LBB0_480:
	s_or_b64 exec, exec, s[4:5]
	ds_read_b128 v[206:209], v149 offset:24576
	ds_read_b128 v[210:213], v151
	ds_read_b128 v[214:217], v149 offset:24608
	ds_read_b128 v[222:225], v151 offset:32
	ds_read_b128 v[226:229], v149 offset:24640
	ds_read_b128 v[230:233], v151 offset:64
	ds_read_b128 v[234:237], v149 offset:24672
	ds_read_b128 v[238:241], v151 offset:96
	s_waitcnt lgkmcnt(6)
	v_mfma_f32_32x32x16_bf16 v[16:31], v[206:209], v[210:213], 0
	s_waitcnt lgkmcnt(4)
	v_mfma_f32_32x32x16_bf16 v[16:31], v[214:217], v[222:225], v[16:31]
	s_waitcnt lgkmcnt(2)
	v_mfma_f32_32x32x16_bf16 v[16:31], v[226:229], v[230:233], v[16:31]
	s_waitcnt lgkmcnt(0)
	v_mfma_f32_32x32x16_bf16 v[16:31], v[234:237], v[238:241], v[16:31]
	s_and_saveexec_b64 s[4:5], s[0:1]
	s_cbranch_execz .LBB0_482
	s_nop 9
	ds_write_b128 v175, v[16:19] offset:16384
	ds_write_b128 v175, v[20:23] offset:17408
	ds_write_b128 v175, v[24:27] offset:18432
	ds_write_b128 v175, v[28:31] offset:19456
.LBB0_482:
	s_or_b64 exec, exec, s[4:5]
	v_add_u32_e32 v176, v153, v171
	s_waitcnt lgkmcnt(0)
	s_barrier
	s_and_saveexec_b64 s[4:5], vcc
	s_cbranch_execz .LBB0_484
	ds_read_b128 v[206:209], v176 offset:16384
	ds_read_b128 v[210:213], v176 offset:17408
	ds_read_b128 v[214:217], v176 offset:18432
	ds_read_b128 v[222:225], v176 offset:19456
	v_and_b32_e32 v243, 0xffff0000, v52
	v_lshlrev_b32_e32 v242, 16, v52
	v_and_b32_e32 v245, 0xffff0000, v53
	v_lshlrev_b32_e32 v244, 16, v53
	s_waitcnt lgkmcnt(3)
	v_pk_add_f32 v[16:17], v[16:17], v[206:207]
	v_pk_add_f32 v[18:19], v[18:19], v[208:209]
	v_pk_add_f32 v[16:17], v[242:243], v[16:17] neg_lo:[0,1] neg_hi:[0,1]
	v_pk_add_f32 v[18:19], v[244:245], v[18:19] neg_lo:[0,1] neg_hi:[0,1]
	s_nop 0
	v_cvt_pk_bf16_f32 v16, v16, v17
	v_cvt_pk_bf16_f32 v17, v18, v19
	ds_write_b64 v174, v[16:17] offset:8704
	v_and_b32_e32 v243, 0xffff0000, v54
	v_lshlrev_b32_e32 v242, 16, v54
	v_and_b32_e32 v245, 0xffff0000, v55
	v_lshlrev_b32_e32 v244, 16, v55
	s_waitcnt lgkmcnt(3)
	v_pk_add_f32 v[20:21], v[20:21], v[210:211]
	v_pk_add_f32 v[22:23], v[22:23], v[212:213]
	v_pk_add_f32 v[20:21], v[242:243], v[20:21] neg_lo:[0,1] neg_hi:[0,1]
	v_pk_add_f32 v[22:23], v[244:245], v[22:23] neg_lo:[0,1] neg_hi:[0,1]
	s_nop 0
	v_cvt_pk_bf16_f32 v20, v20, v21
	v_cvt_pk_bf16_f32 v21, v22, v23
	ds_write_b64 v174, v[20:21] offset:8720
	v_and_b32_e32 v243, 0xffff0000, v48
	v_lshlrev_b32_e32 v242, 16, v48
	v_and_b32_e32 v245, 0xffff0000, v49
	v_lshlrev_b32_e32 v244, 16, v49
	s_waitcnt lgkmcnt(3)
	v_pk_add_f32 v[24:25], v[24:25], v[214:215]
	v_pk_add_f32 v[26:27], v[26:27], v[216:217]
	v_pk_add_f32 v[24:25], v[242:243], v[24:25] neg_lo:[0,1] neg_hi:[0,1]
	v_pk_add_f32 v[26:27], v[244:245], v[26:27] neg_lo:[0,1] neg_hi:[0,1]
	s_nop 0
	v_cvt_pk_bf16_f32 v24, v24, v25
	v_cvt_pk_bf16_f32 v25, v26, v27
	ds_write_b64 v174, v[24:25] offset:8736
	v_and_b32_e32 v243, 0xffff0000, v50
	v_lshlrev_b32_e32 v242, 16, v50
	v_and_b32_e32 v245, 0xffff0000, v51
	v_lshlrev_b32_e32 v244, 16, v51
	s_waitcnt lgkmcnt(3)
	v_pk_add_f32 v[28:29], v[28:29], v[222:223]
	v_pk_add_f32 v[30:31], v[30:31], v[224:225]
	v_pk_add_f32 v[28:29], v[242:243], v[28:29] neg_lo:[0,1] neg_hi:[0,1]
	v_pk_add_f32 v[30:31], v[244:245], v[30:31] neg_lo:[0,1] neg_hi:[0,1]
	s_nop 0
	v_cvt_pk_bf16_f32 v28, v28, v29
	v_cvt_pk_bf16_f32 v29, v30, v31
	ds_write_b64 v174, v[28:29] offset:8752
.LBB0_484:
	s_or_b64 exec, exec, s[4:5]
	v_add_u32_e32 v178, v147, v155
	s_waitcnt lgkmcnt(0)
	s_barrier
	ds_read_b128 v[16:19], v178 offset:8704
	ds_read_b128 v[20:23], v178 offset:8736
	ds_read_b128 v[24:27], v178 offset:8768
	ds_read_b128 v[28:31], v178 offset:8800
	s_waitcnt vmcnt(25)
	v_pk_mul_f32 v[14:15], v[14:15], v[142:143] op_sel_hi:[1,0]
	v_pk_mul_f32 v[12:13], v[12:13], v[142:143] op_sel_hi:[1,0]
	v_pk_mul_f32 v[10:11], v[10:11], v[142:143] op_sel_hi:[1,0]
	v_pk_mul_f32 v[8:9], v[8:9], v[142:143] op_sel_hi:[1,0]
	v_pk_mul_f32 v[6:7], v[6:7], v[142:143] op_sel_hi:[1,0]
	v_pk_mul_f32 v[4:5], v[4:5], v[142:143] op_sel_hi:[1,0]
	v_pk_mul_f32 v[2:3], v[2:3], v[142:143] op_sel_hi:[1,0]
	v_pk_mul_f32 v[0:1], v[0:1], v[142:143] op_sel_hi:[1,0]
	s_waitcnt lgkmcnt(3)
	s_nop 0
	v_mfma_f32_32x32x16_bf16 v[0:15], v[44:47], v[16:19], v[0:15]
	s_waitcnt lgkmcnt(2)
	v_mfma_f32_32x32x16_bf16 v[0:15], v[40:43], v[20:23], v[0:15]
	s_waitcnt lgkmcnt(1)
	v_mfma_f32_32x32x16_bf16 v[0:15], v[36:39], v[24:27], v[0:15]
	s_waitcnt lgkmcnt(0)
	v_mfma_f32_32x32x16_bf16 v[0:15], v[32:35], v[28:31], v[0:15]
	s_add_i32 s6, s15, -2
	s_cmp_eq_u32 s8, 0x2a0000
	s_cselect_b64 s[10:11], -1, 0
	s_and_b64 s[4:5], s[10:11], exec
	s_cselect_b32 s20, 0x80, s6
	s_add_i32 s6, s20, s14
	s_lshl_b64 s[22:23], s[6:7], 14
	v_lshl_add_u64 v[16:17], v[162:163], 0, s[22:23]
	v_add_co_u32_e64 v18, s[4:5], s18, v16
	v_lshl_add_u64 v[20:21], v[164:165], 0, s[22:23]
	s_nop 0
	v_addc_co_u32_e64 v19, s[4:5], 0, v17, s[4:5]
	global_load_dwordx4 v[32:35], v[18:19], off offset:-4096
	global_load_dwordx4 v[36:39], v[18:19], off
	v_add_co_u32_e64 v18, s[4:5], s19, v16
	s_ashr_i32 s21, s20, 31
	s_nop 0
	v_addc_co_u32_e64 v19, s[4:5], 0, v17, s[4:5]
	global_load_dwordx4 v[40:43], v[18:19], off
	global_load_dwordx4 v[44:47], v[20:21], off
	v_add_co_u32_e64 v18, s[4:5], s18, v20
	s_nop 1
	v_addc_co_u32_e64 v19, s[4:5], 0, v21, s[4:5]
	global_load_dwordx4 v[48:51], v[18:19], off offset:-4096
	global_load_dwordx4 v[52:55], v[18:19], off
	v_add_co_u32_e64 v18, s[4:5], s19, v20
	s_nop 1
	v_addc_co_u32_e64 v19, s[4:5], 0, v21, s[4:5]
	s_lshl_b64 s[4:5], s[20:21], 2
	s_add_u32 s4, s16, s4
	v_lshl_add_u64 v[20:21], v[166:167], 0, s[22:23]
	global_load_dwordx4 v[68:71], v[18:19], off
	global_load_dwordx4 v[82:85], v[20:21], off
	s_addc_u32 s5, s17, s5
	global_load_dwordx4 v[64:67], v[16:17], off
	global_load_dword v177, v157, s[4:5]
	ds_write_b128 v146, v[94:97] offset:24576
	ds_write_b128 v148, v[56:59] offset:24576
	ds_write_b128 v150, v[60:63] offset:24576
	ds_write_b128 v152, v[72:75] offset:24576
	ds_write_b128 v154, v[76:79] offset:41984
	ds_write_b128 v156, v[86:89] offset:41984
	ds_write_b128 v158, v[90:93] offset:41984
	ds_write_b128 v160, v[106:109] offset:41984
	ds_write_b128 v154, v[110:113] offset:60416
	v_cvt_pk_bf16_f32 v16, v0, v1
	v_cvt_pk_bf16_f32 v17, v2, v3
	v_cvt_pk_bf16_f32 v18, v4, v5
	v_cvt_pk_bf16_f32 v19, v6, v7
	ds_write2_b64 v159, v[16:17], v[18:19] offset1:2
	v_cvt_pk_bf16_f32 v16, v8, v9
	v_cvt_pk_bf16_f32 v17, v10, v11
	v_cvt_pk_bf16_f32 v18, v12, v13
	v_cvt_pk_bf16_f32 v19, v14, v15
	ds_write2_b64 v159, v[16:17], v[18:19] offset0:4 offset1:6
	s_waitcnt lgkmcnt(0)
	s_barrier
	ds_read_b128 v[76:79], v161 offset:41984
	ds_read_b128 v[72:75], v161 offset:42016
	ds_read_b128 v[60:63], v161 offset:42048
	ds_read_b128 v[56:59], v161 offset:42080
	s_and_saveexec_b64 s[4:5], vcc
	s_cbranch_execz .LBB0_486
	ds_read2_b64 v[90:93], v179 offset0:128 offset1:130
	ds_read2_b64 v[86:89], v179 offset0:132 offset1:134

.LBB0_488:
	s_or_b64 exec, exec, s[4:5]
	s_waitcnt lgkmcnt(0)
	s_barrier
	s_and_saveexec_b64 s[4:5], vcc
	s_cbranch_execz .LBB0_490
	ds_read_b128 v[206:209], v176 offset:16384
	ds_read_b128 v[210:213], v176 offset:17408
	ds_read_b128 v[214:217], v176 offset:18432
	ds_read_b128 v[222:225], v176 offset:19456
	v_and_b32_e32 v243, 0xffff0000, v90
	v_lshlrev_b32_e32 v242, 16, v90
	v_and_b32_e32 v245, 0xffff0000, v91
	v_lshlrev_b32_e32 v244, 16, v91
	s_waitcnt lgkmcnt(3)
	v_pk_add_f32 v[16:17], v[16:17], v[206:207]
	v_pk_add_f32 v[18:19], v[18:19], v[208:209]
	v_pk_add_f32 v[16:17], v[242:243], v[16:17] neg_lo:[0,1] neg_hi:[0,1]
	v_pk_add_f32 v[18:19], v[244:245], v[18:19] neg_lo:[0,1] neg_hi:[0,1]
	s_nop 0
	v_cvt_pk_bf16_f32 v16, v16, v17
	v_cvt_pk_bf16_f32 v17, v18, v19
	ds_write_b64 v174, v[16:17] offset:8704
	v_and_b32_e32 v243, 0xffff0000, v92
	v_lshlrev_b32_e32 v242, 16, v92
	v_and_b32_e32 v245, 0xffff0000, v93
	v_lshlrev_b32_e32 v244, 16, v93
	s_waitcnt lgkmcnt(3)
	v_pk_add_f32 v[20:21], v[20:21], v[210:211]
	v_pk_add_f32 v[22:23], v[22:23], v[212:213]
	v_pk_add_f32 v[20:21], v[242:243], v[20:21] neg_lo:[0,1] neg_hi:[0,1]
	v_pk_add_f32 v[22:23], v[244:245], v[22:23] neg_lo:[0,1] neg_hi:[0,1]
	s_nop 0
	v_cvt_pk_bf16_f32 v20, v20, v21
	v_cvt_pk_bf16_f32 v21, v22, v23
	ds_write_b64 v174, v[20:21] offset:8720
	v_and_b32_e32 v243, 0xffff0000, v86
	v_lshlrev_b32_e32 v242, 16, v86
	v_and_b32_e32 v245, 0xffff0000, v87
	v_lshlrev_b32_e32 v244, 16, v87
	s_waitcnt lgkmcnt(3)
	v_pk_add_f32 v[24:25], v[24:25], v[214:215]
	v_pk_add_f32 v[26:27], v[26:27], v[216:217]
	v_pk_add_f32 v[24:25], v[242:243], v[24:25] neg_lo:[0,1] neg_hi:[0,1]
	v_pk_add_f32 v[26:27], v[244:245], v[26:27] neg_lo:[0,1] neg_hi:[0,1]
	s_nop 0
	v_cvt_pk_bf16_f32 v24, v24, v25
	v_cvt_pk_bf16_f32 v25, v26, v27
	ds_write_b64 v174, v[24:25] offset:8736
	v_and_b32_e32 v243, 0xffff0000, v88
	v_lshlrev_b32_e32 v242, 16, v88
	v_and_b32_e32 v245, 0xffff0000, v89
	v_lshlrev_b32_e32 v244, 16, v89
	s_waitcnt lgkmcnt(3)
	v_pk_add_f32 v[28:29], v[28:29], v[222:223]
	v_pk_add_f32 v[30:31], v[30:31], v[224:225]
	v_pk_add_f32 v[28:29], v[242:243], v[28:29] neg_lo:[0,1] neg_hi:[0,1]
	v_pk_add_f32 v[30:31], v[244:245], v[30:31] neg_lo:[0,1] neg_hi:[0,1]
	s_nop 0
	v_cvt_pk_bf16_f32 v28, v28, v29
	v_cvt_pk_bf16_f32 v29, v30, v31
	ds_write_b64 v174, v[28:29] offset:8752
.LBB0_490:
	s_or_b64 exec, exec, s[4:5]
	s_waitcnt lgkmcnt(0)
	s_barrier
	s_nop 1
	ds_read_b128 v[16:19], v178 offset:8704
	ds_read_b128 v[20:23], v178 offset:8736
	ds_read_b128 v[24:27], v178 offset:8768
	ds_read_b128 v[28:31], v178 offset:8800
	v_pk_mul_f32 v[0:1], v[142:143], v[0:1] op_sel:[1,0]
	v_pk_mul_f32 v[14:15], v[142:143], v[14:15] op_sel:[1,0]
	v_pk_mul_f32 v[12:13], v[142:143], v[12:13] op_sel:[1,0]
	v_pk_mul_f32 v[10:11], v[142:143], v[10:11] op_sel:[1,0]
	v_pk_mul_f32 v[8:9], v[142:143], v[8:9] op_sel:[1,0]
	v_pk_mul_f32 v[6:7], v[142:143], v[6:7] op_sel:[1,0]
	v_pk_mul_f32 v[4:5], v[142:143], v[4:5] op_sel:[1,0]
	v_pk_mul_f32 v[2:3], v[142:143], v[2:3] op_sel:[1,0]
	s_waitcnt lgkmcnt(3)
	s_nop 0
	v_mfma_f32_32x32x16_bf16 v[0:15], v[76:79], v[16:19], v[0:15]
	s_waitcnt lgkmcnt(2)
	v_mfma_f32_32x32x16_bf16 v[0:15], v[72:75], v[20:23], v[0:15]
	s_waitcnt lgkmcnt(1)
	v_mfma_f32_32x32x16_bf16 v[0:15], v[60:63], v[24:27], v[0:15]
	s_waitcnt lgkmcnt(0)
	v_mfma_f32_32x32x16_bf16 v[0:15], v[56:59], v[28:31], v[0:15]
	s_add_i32 s6, s15, -1
	s_and_b64 s[4:5], s[10:11], exec
	s_cselect_b32 s20, 0x80, s6
	s_add_i32 s6, s20, s14
	s_lshl_b64 s[22:23], s[6:7], 14
	v_lshl_add_u64 v[16:17], v[162:163], 0, s[22:23]
	v_add_co_u32_e64 v18, s[4:5], s18, v16
	v_lshl_add_u64 v[20:21], v[164:165], 0, s[22:23]
	s_nop 0
	v_addc_co_u32_e64 v19, s[4:5], 0, v17, s[4:5]
	global_load_dwordx4 v[56:59], v[18:19], off offset:-4096
	global_load_dwordx4 v[60:63], v[18:19], off
	v_add_co_u32_e64 v18, s[4:5], s19, v16
	s_ashr_i32 s21, s20, 31
	s_nop 0
	v_addc_co_u32_e64 v19, s[4:5], 0, v17, s[4:5]
	global_load_dwordx4 v[72:75], v[18:19], off
	global_load_dwordx4 v[76:79], v[20:21], off
	v_add_co_u32_e64 v18, s[4:5], s18, v20
	s_nop 1
	v_addc_co_u32_e64 v19, s[4:5], 0, v21, s[4:5]
	global_load_dwordx4 v[86:89], v[18:19], off offset:-4096
	global_load_dwordx4 v[90:93], v[18:19], off
	v_add_co_u32_e64 v18, s[4:5], s19, v20
	s_nop 1
	v_addc_co_u32_e64 v19, s[4:5], 0, v21, s[4:5]
	s_lshl_b64 s[4:5], s[20:21], 2
	s_add_u32 s4, s16, s4
	v_lshl_add_u64 v[20:21], v[166:167], 0, s[22:23]
	global_load_dwordx4 v[106:109], v[18:19], off
	global_load_dwordx4 v[110:113], v[20:21], off
	s_addc_u32 s5, s17, s5
	global_load_dwordx4 v[94:97], v[16:17], off
	global_load_dword v143, v157, s[4:5]
	s_waitcnt vmcnt(37)
	ds_write_b128 v146, v[130:133] offset:24576
	s_waitcnt vmcnt(43)
	ds_write_b128 v148, v[98:101] offset:24576
	s_waitcnt vmcnt(42)
	ds_write_b128 v150, v[102:105] offset:24576
	s_waitcnt vmcnt(41)
	ds_write_b128 v152, v[114:117] offset:24576
	s_waitcnt vmcnt(40)
	ds_write_b128 v154, v[118:121] offset:41984
	s_waitcnt vmcnt(39)
	ds_write_b128 v156, v[122:125] offset:41984
	s_waitcnt vmcnt(38)
	ds_write_b128 v158, v[126:129] offset:41984
	s_waitcnt vmcnt(37)
	ds_write_b128 v160, v[134:137] offset:41984
	s_waitcnt vmcnt(36)
	ds_write_b128 v154, v[138:141] offset:60416
	v_cvt_pk_bf16_f32 v16, v0, v1
	v_cvt_pk_bf16_f32 v17, v2, v3
	v_cvt_pk_bf16_f32 v18, v4, v5
	v_cvt_pk_bf16_f32 v19, v6, v7
	ds_write2_b64 v159, v[16:17], v[18:19] offset1:2
	v_cvt_pk_bf16_f32 v16, v8, v9
	v_cvt_pk_bf16_f32 v17, v10, v11
	v_cvt_pk_bf16_f32 v18, v12, v13
	v_cvt_pk_bf16_f32 v19, v14, v15
	ds_write2_b64 v159, v[16:17], v[18:19] offset0:4 offset1:6
	s_waitcnt lgkmcnt(0)
	s_barrier
	ds_read_b128 v[118:121], v161 offset:41984
	ds_read_b128 v[114:117], v161 offset:42016
	ds_read_b128 v[102:105], v161 offset:42048
	ds_read_b128 v[98:101], v161 offset:42080
	s_and_saveexec_b64 s[4:5], vcc
	s_cbranch_execz .LBB0_492
	ds_read2_b64 v[126:129], v179 offset0:128 offset1:130
	ds_read2_b64 v[122:125], v179 offset0:132 offset1:134

.LBB0_494:
	s_or_b64 exec, exec, s[4:5]
	s_waitcnt lgkmcnt(0)
	s_barrier
	s_and_saveexec_b64 s[4:5], vcc
	s_cbranch_execz .LBB0_477
	ds_read_b128 v[206:209], v176 offset:16384
	ds_read_b128 v[210:213], v176 offset:17408
	ds_read_b128 v[214:217], v176 offset:18432
	ds_read_b128 v[222:225], v176 offset:19456
	v_and_b32_e32 v243, 0xffff0000, v126
	v_lshlrev_b32_e32 v242, 16, v126
	v_and_b32_e32 v245, 0xffff0000, v127
	v_lshlrev_b32_e32 v244, 16, v127
	s_waitcnt lgkmcnt(3)
	v_pk_add_f32 v[16:17], v[16:17], v[206:207]
	v_pk_add_f32 v[18:19], v[18:19], v[208:209]
	v_pk_add_f32 v[16:17], v[242:243], v[16:17] neg_lo:[0,1] neg_hi:[0,1]
	v_pk_add_f32 v[18:19], v[244:245], v[18:19] neg_lo:[0,1] neg_hi:[0,1]
	s_nop 0
	v_cvt_pk_bf16_f32 v16, v16, v17
	v_cvt_pk_bf16_f32 v17, v18, v19
	ds_write_b64 v174, v[16:17] offset:8704
	v_and_b32_e32 v243, 0xffff0000, v128
	v_lshlrev_b32_e32 v242, 16, v128
	v_and_b32_e32 v245, 0xffff0000, v129
	v_lshlrev_b32_e32 v244, 16, v129
	s_waitcnt lgkmcnt(3)
	v_pk_add_f32 v[20:21], v[20:21], v[210:211]
	v_pk_add_f32 v[22:23], v[22:23], v[212:213]
	v_pk_add_f32 v[20:21], v[242:243], v[20:21] neg_lo:[0,1] neg_hi:[0,1]
	v_pk_add_f32 v[22:23], v[244:245], v[22:23] neg_lo:[0,1] neg_hi:[0,1]
	s_nop 0
	v_cvt_pk_bf16_f32 v20, v20, v21
	v_cvt_pk_bf16_f32 v21, v22, v23
	ds_write_b64 v174, v[20:21] offset:8720
	v_and_b32_e32 v243, 0xffff0000, v122
	v_lshlrev_b32_e32 v242, 16, v122
	v_and_b32_e32 v245, 0xffff0000, v123
	v_lshlrev_b32_e32 v244, 16, v123
	s_waitcnt lgkmcnt(3)
	v_pk_add_f32 v[24:25], v[24:25], v[214:215]
	v_pk_add_f32 v[26:27], v[26:27], v[216:217]
	v_pk_add_f32 v[24:25], v[242:243], v[24:25] neg_lo:[0,1] neg_hi:[0,1]
	v_pk_add_f32 v[26:27], v[244:245], v[26:27] neg_lo:[0,1] neg_hi:[0,1]
	s_nop 0
	v_cvt_pk_bf16_f32 v24, v24, v25
	v_cvt_pk_bf16_f32 v25, v26, v27
	ds_write_b64 v174, v[24:25] offset:8736
	v_and_b32_e32 v243, 0xffff0000, v124
	v_lshlrev_b32_e32 v242, 16, v124
	v_and_b32_e32 v245, 0xffff0000, v125
	v_lshlrev_b32_e32 v244, 16, v125
	s_waitcnt lgkmcnt(3)
	v_pk_add_f32 v[28:29], v[28:29], v[222:223]
	v_pk_add_f32 v[30:31], v[30:31], v[224:225]
	v_pk_add_f32 v[28:29], v[242:243], v[28:29] neg_lo:[0,1] neg_hi:[0,1]
	v_pk_add_f32 v[30:31], v[244:245], v[30:31] neg_lo:[0,1] neg_hi:[0,1]
	s_nop 0
	v_cvt_pk_bf16_f32 v28, v28, v29
	v_cvt_pk_bf16_f32 v29, v30, v31
	ds_write_b64 v174, v[28:29] offset:8752
	s_branch .LBB0_477
